# v2 plus gla_pre next-item q/k/gate-code loads issued at top of current item (one item ahead), top-of-item vmcnt(0) waits skipped after first item
# speedup vs baseline: 1.0037x; 1.0006x over previous
; #define LAS __attribute__((address_space(3)))
; __device__ __forceinline__ void phase_gla_pre(const Params& P, LAS unsigned char* lds, bool dry) {
;     ...
;         if (tid < 256) *(LAS f32x4*)(Llr + 4 * tid) = rl;
;         bf16x8 bhi = (bf16x8){0, 0, 0, 0, 0, 0, 0, 0}, blo = bhi;
;         if (g < 2) { f32x4 w0, w1;
; #pragma unroll
;             for (int j = 0; j < 4; ++j) { w0[j] = P.w_gate_up[(8 * g + j) * 512 + h * 128 + 16 * w + fr]; w1[j] = P.w_gate_up[(8 * g + 4 + j) * 512 + h * 128 + 16 * w + fr]; }
;             split8(w0, w1, bhi, blo); }
;         const float bg = P.b_gate_up[h * 128 + 16 * w + fr];
;     ...
;         { const int ni = item + gridDim.x;
;           if (ni < 2048) { const int nbh = ni >> 6, nrow0 = (nbh >> 2) * SEQ + (ni & 63) * 64; const bf16_t* p_ = PJ + ((size_t)nbh * SEQ + (ni & 63) * 64 + te) * 128 + 16 * kc;
;             rq[0] = *(const u32x4*)(p_ + T_Q); rq[1] = *(const u32x4*)(p_ + T_Q + 8); rk[0] = *(const u32x4*)(p_ + T_K); rk[1] = *(const u32x4*)(p_ + T_K + 8);
;             if (tid < 256) rl = *(const f32x4*)(LR + (size_t)nrow0 * 16 + 4 * tid); } }
.LBB0_480:
	s_and_saveexec_b64 s[36:37], s[4:5]
	s_cbranch_execz .LBB0_482
	s_cmp_lg_u32 s98, 0
	s_cbranch_scc1 .Lp2_nowait0
	s_waitcnt vmcnt(0)
.Lp2_nowait0:
	ds_write_b128 v88, v[0:3]
.LBB0_482:
	s_or_b64 exec, exec, s[36:37]
	s_add_i32 s99, s80, s38
	s_cmpk_gt_i32 s99, 0x7ff
	s_cbranch_scc1 .Lp2_nopf
	s_ashr_i32 s100, s99, 6
	s_ashr_i32 s101, s100, 31
	s_lshl_b64 s[100:101], s[100:101], 20
	s_add_i32 s99, s3, s1
	s_and_b32 s99, s99, 0xfc0
	v_mov_b32_e32 v170, s99
	v_mov_b32_e32 v171, 0
	v_lshl_add_u64 v[170:171], v[48:49], 0, v[170:171]
	v_lshlrev_b64 v[170:171], 8, v[170:171]
	v_lshl_add_u64 v[172:173], v[52:53], 0, s[100:101]
	v_lshl_add_u64 v[172:173], v[172:173], 0, v[170:171]
	v_lshl_add_u64 v[176:177], v[172:173], 0, s[76:77]
	v_lshl_add_u64 v[178:179], v[172:173], 0, s[78:79]
	global_load_dwordx4 v[154:157], v[176:177], off
	global_load_dwordx4 v[158:161], v[176:177], off offset:16
	global_load_dwordx4 v[162:165], v[178:179], off
	global_load_dwordx4 v[166:169], v[178:179], off offset:16
	s_and_b32 s100, s84, 0xfffff000
	s_or_b32 s100, s100, s99
	s_ashr_i32 s101, s100, 31
	s_lshl_b64 s[100:101], s[100:101], 6
	v_lshl_add_u64 v[174:175], v[56:57], 0, s[100:101]
	s_and_saveexec_b64 s[100:101], s[4:5]
	global_load_dwordx4 v[150:153], v[174:175], off
	s_or_b64 exec, exec, s[100:101]
.Lp2_nopf:
	s_ashr_i32 s82, s80, 6
	s_lshl_b32 s36, s82, 7
	s_and_b32 s42, s36, 0x180
	v_mov_b32_e32 v32, 0
	v_mov_b32_e32 v24, 0
	v_mov_b32_e32 v25, 0
	v_mov_b32_e32 v26, 0
	v_mov_b32_e32 v27, 0
	v_mov_b32_e32 v20, 0
	v_mov_b32_e32 v21, 0
	v_mov_b32_e32 v22, 0
	v_mov_b32_e32 v23, 0
	s_cmp_lg_u32 s98, 0
	s_cbranch_scc1 .Lp2_hoisted
	s_and_saveexec_b64 s[36:37], s[6:7]
	s_cbranch_execz .LBB0_484
	v_or_b32_e32 v28, s42, v80
	v_or_b32_e32 v26, 0x400, v28
	v_add_u32_e32 v20, v28, v81
	v_add_u32_e32 v24, v26, v81
	v_add_u32_e32 v26, v26, v82
	v_or_b32_e32 v30, 0x600, v28
	v_ashrrev_i32_e32 v21, 31, v20
	v_add_u32_e32 v22, v28, v82
	v_ashrrev_i32_e32 v25, 31, v24
	v_ashrrev_i32_e32 v27, 31, v26
	v_add_u32_e32 v28, v30, v81
	v_add_u32_e32 v30, v30, v82
	v_lshl_add_u64 v[20:21], v[20:21], 2, s[54:55]
	v_ashrrev_i32_e32 v23, 31, v22
	v_lshl_add_u64 v[24:25], v[24:25], 2, s[54:55]
	v_lshl_add_u64 v[26:27], v[26:27], 2, s[54:55]
	v_ashrrev_i32_e32 v29, 31, v28
	v_ashrrev_i32_e32 v31, 31, v30
	v_lshl_add_u64 v[22:23], v[22:23], 2, s[54:55]
	v_lshl_add_u64 v[28:29], v[28:29], 2, s[54:55]
	v_lshl_add_u64 v[30:31], v[30:31], 2, s[54:55]
	global_load_dword v34, v[20:21], off
	global_load_dword v36, v[22:23], off
	global_load_dword v37, v[22:23], off offset:2048
	s_nop 0
	global_load_dword v24, v[24:25], off
	s_nop 0
	global_load_dword v26, v[26:27], off
	s_nop 0
	global_load_dword v25, v[28:29], off
	global_load_dword v27, v[30:31], off
	global_load_dword v35, v[20:21], off offset:2048
	s_waitcnt vmcnt(7)
	v_and_b32_sdwa v20, v34, v95 dst_sel:DWORD dst_unused:UNUSED_PAD src0_sel:WORD_1 src1_sel:DWORD
	s_waitcnt vmcnt(6)
	v_and_b32_sdwa v22, v36, v95 dst_sel:DWORD dst_unused:UNUSED_PAD src0_sel:WORD_1 src1_sel:DWORD
	s_waitcnt vmcnt(5)
	v_and_b32_sdwa v21, v37, v95 dst_sel:DWORD dst_unused:UNUSED_PAD src0_sel:WORD_1 src1_sel:DWORD
	v_add3_u32 v33, v34, v20, s86
	s_waitcnt vmcnt(4)
	v_and_b32_sdwa v29, v24, v95 dst_sel:DWORD dst_unused:UNUSED_PAD src0_sel:WORD_1 src1_sel:DWORD
	s_waitcnt vmcnt(2)
	v_and_b32_sdwa v20, v25, v95 dst_sel:DWORD dst_unused:UNUSED_PAD src0_sel:WORD_1 src1_sel:DWORD
	s_waitcnt vmcnt(1)
	v_and_b32_sdwa v31, v27, v95 dst_sel:DWORD dst_unused:UNUSED_PAD src0_sel:WORD_1 src1_sel:DWORD
	s_waitcnt vmcnt(0)
	v_and_b32_sdwa v23, v35, v95 dst_sel:DWORD dst_unused:UNUSED_PAD src0_sel:WORD_1 src1_sel:DWORD
	v_and_b32_sdwa v38, v26, v95 dst_sel:DWORD dst_unused:UNUSED_PAD src0_sel:WORD_1 src1_sel:DWORD
	v_add3_u32 v30, v37, v21, s86
	v_add3_u32 v22, v36, v22, s86
	v_add3_u32 v23, v35, v23, s86
	v_add3_u32 v40, v25, v20, s86
	v_add3_u32 v41, v24, v29, s86
	v_add3_u32 v42, v27, v31, s86
	v_add3_u32 v43, v26, v38, s86
	v_and_b32_e32 v28, 0xffff0000, v33
	v_and_b32_e32 v21, 0xffff0000, v30
	v_and_b32_e32 v20, 0xffff0000, v22
	v_cvt_pk_bf16_f32 v22, v36, v37
	v_and_b32_e32 v29, 0xffff0000, v23
	v_and_b32_e32 v31, 0xffff0000, v40
	v_and_b32_e32 v30, 0xffff0000, v41
	v_and_b32_e32 v39, 0xffff0000, v42
	v_and_b32_e32 v38, 0xffff0000, v43
	v_pk_add_f32 v[36:37], v[36:37], v[20:21] neg_lo:[0,1] neg_hi:[0,1]
	v_pk_add_f32 v[28:29], v[34:35], v[28:29] neg_lo:[0,1] neg_hi:[0,1]
	v_pk_add_f32 v[24:25], v[24:25], v[30:31] neg_lo:[0,1] neg_hi:[0,1]
	v_pk_add_f32 v[26:27], v[26:27], v[38:39] neg_lo:[0,1] neg_hi:[0,1]
	v_cvt_pk_bf16_f32 v20, v34, v35
	v_bfe_u32 v23, v37, 16, 1
	v_bfe_u32 v30, v36, 16, 1
	v_bfe_u32 v31, v29, 16, 1
	v_bfe_u32 v33, v28, 16, 1
	v_bfe_u32 v34, v25, 16, 1
	v_bfe_u32 v35, v24, 16, 1
	v_bfe_u32 v38, v27, 16, 1
	v_bfe_u32 v39, v26, 16, 1
	v_add3_u32 v30, v36, v30, s86
	v_add3_u32 v23, v37, v23, s86
	v_add3_u32 v36, v26, v39, s86
	v_add3_u32 v27, v27, v38, s86
	v_add3_u32 v35, v24, v35, s86
	v_add3_u32 v25, v25, v34, s86
	v_add3_u32 v24, v28, v33, s86
	v_add3_u32 v28, v29, v31, s86
	v_perm_b32 v21, v40, v41, s88
	v_perm_b32 v26, v23, v30, s88
	v_perm_b32 v24, v28, v24, s88
	v_perm_b32 v25, v25, v35, s88
	v_perm_b32 v27, v27, v36, s88
	v_perm_b32 v23, v42, v43, s88

; #define LAS __attribute__((address_space(3)))
; __device__ __forceinline__ void phase_gla_pre(const Params& P, LAS unsigned char* lds, bool dry) {
;     ...
;         for (int tt = 0; tt < 4; ++tt) {
;             bf16x8 ahi = (bf16x8){0, 0, 0, 0, 0, 0, 0, 0}, alo = ahi;
;             if (g < 2) { const f32x4 l0 = *(const LAS f32x4*)(Llr + (16 * tt + fr) * 16 + 8 * g), l1 = *(const LAS f32x4*)(Llr + (16 * tt + fr) * 16 + 8 * g + 4); split8(l0, l1, ahi, alo); }
;             f32x4 acc = (f32x4){bg, bg, bg, bg};
;             acc = __builtin_amdgcn_mfma_f32_16x16x32_bf16(alo, bhi, acc, 0, 0, 0); acc = __builtin_amdgcn_mfma_f32_16x16x32_bf16(ahi, blo, acc, 0, 0, 0); acc = __builtin_amdgcn_mfma_f32_16x16x32_bf16(ahi, bhi, acc, 0, 0, 0);
;             float pr[4];
; #pragma unroll
;             for (int r = 0; r < 4; ++r) { const float lg = acc[r]; const float ls = fminf(lg, 0.f) - __logf(1.0f + __expf(-fabsf(lg))); pr[r] = ls * (1.0f / 16.0f) + (r ? pr[r - 1] : 0.f); }
;             const float T = pr[3];
;             const float u1 = __shfl_up(T, 16), s1 = T + (g >= 1 ? u1 : 0.f);
;             const float u2 = __shfl_up(s1, 32), s2 = s1 + (g >= 2 ? u2 : 0.f);
;             const float base = run + (s2 - T); run += __shfl(s2, 48 + fr);
; #pragma unroll
;             for (int r = 0; r < 4; ++r) *(LAS float*)(Lb + (16 * tt + 4 * g + r) * BP + (16 * w + fr) * 4) = base + pr[r];
.LBB0_486:
	s_or_b64 exec, exec, s[36:37]
	s_cmp_lg_u32 s98, 0
	s_cbranch_scc1 .Lp2_nowait1
	s_waitcnt vmcnt(0)
.Lp2_nowait1:
	v_mov_b32_e32 v140, v20
	v_mov_b32_e32 v141, v21
	v_mov_b32_e32 v142, v22
	v_mov_b32_e32 v143, v23
	v_mov_b32_e32 v144, v24
	v_mov_b32_e32 v145, v25
	v_mov_b32_e32 v146, v26
	v_mov_b32_e32 v147, v27
	v_mov_b32_e32 v148, v28
	s_and_b32 s98, s38, 0xff
	s_cselect_b32 s98, 0, 1
	v_mov_b32_e32 v29, v28
	v_mov_b32_e32 v30, v28
	v_mov_b32_e32 v31, v28
	v_mov_b32_e32 v40, 0
	v_mov_b32_e32 v41, 0
	v_mfma_f32_16x16x32_bf16 v[32:35], v[32:35], v[20:23], v[28:31]
	v_mfma_f32_16x16x32_bf16 v[32:35], v[36:39], v[24:27], v[32:35]
	v_mfma_f32_16x16x32_bf16 v[32:35], v[36:39], v[20:23], v[32:35]
	s_nop 7
	v_max_f32_e32 v36, v32, v32
	v_mul_f32_e64 v32, |v32|, s89
	v_exp_f32_e32 v32, v32
	v_mul_f32_e64 v37, |v33|, s89
	v_exp_f32_e32 v37, v37
	v_min_f32_e32 v36, 0, v36
	v_add_f32_e32 v32, 1.0, v32
	v_cmp_gt_f32_e32 vcc, s90, v32
	v_add_f32_e32 v37, 1.0, v37
	v_cmp_gt_f32_e64 s[36:37], s90, v37
	v_cndmask_b32_e64 v38, 0, 32, vcc
	v_ldexp_f32 v32, v32, v38
	v_log_f32_e32 v32, v32
	v_cndmask_b32_e64 v39, 0, 32, s[36:37]
	v_ldexp_f32 v37, v37, v39
	v_log_f32_e32 v37, v37
	v_mul_f32_e32 v39, 0x3f317217, v32
	v_fma_f32 v39, v32, s91, -v39
	v_fmac_f32_e32 v39, 0x3377d1cf, v32
	v_cndmask_b32_e32 v38, 0, v97, vcc
	v_fmac_f32_e32 v39, 0x3f317217, v32
	v_cmp_lt_f32_e64 vcc, |v32|, s92
	v_max_f32_e32 v33, v33, v33
	v_min_f32_e32 v33, 0, v33
	v_cndmask_b32_e32 v32, v32, v39, vcc
	v_sub_f32_e32 v32, v32, v38
	v_sub_f32_e32 v32, v36, v32
	v_mul_f32_e32 v36, 0x3f317217, v37
	v_fma_f32 v36, v37, s91, -v36
	v_fmac_f32_e32 v36, 0x3377d1cf, v37
	v_fmac_f32_e32 v36, 0x3f317217, v37
	v_cmp_lt_f32_e64 vcc, |v37|, s92
	v_cndmask_b32_e64 v38, 0, v97, s[36:37]
	v_fma_f32 v32, v32, s93, 0
	v_cndmask_b32_e32 v36, v37, v36, vcc
	v_mul_f32_e64 v37, |v34|, s89
	v_exp_f32_e32 v37, v37
	v_sub_f32_e32 v36, v36, v38
	v_sub_f32_e32 v33, v33, v36
	v_mov_b32_e32 v39, 0
	v_add_f32_e32 v36, 1.0, v37
	v_cmp_gt_f32_e32 vcc, s90, v36
	s_nop 1
	v_cndmask_b32_e64 v37, 0, 32, vcc
	v_ldexp_f32 v36, v36, v37
	v_log_f32_e32 v36, v36
	v_fmamk_f32 v37, v33, 0x3d800000, v32
	v_max_f32_e32 v33, v34, v34
	v_cndmask_b32_e32 v38, 0, v97, vcc
	v_mul_f32_e32 v34, 0x3f317217, v36
	v_fma_f32 v34, v36, s91, -v34
	v_fmac_f32_e32 v34, 0x3377d1cf, v36
	v_fmac_f32_e32 v34, 0x3f317217, v36
	v_cmp_lt_f32_e64 s[36:37], |v36|, s92
	v_min_f32_e32 v33, 0, v33
	s_nop 0
	v_cndmask_b32_e64 v34, v36, v34, s[36:37]
	v_mul_f32_e64 v36, |v35|, s89
	v_exp_f32_e32 v36, v36
	v_sub_f32_e32 v34, v34, v38
	v_sub_f32_e32 v33, v33, v34
	v_add_u32_e32 v38, 0x8800, v98
	v_add_f32_e32 v34, 1.0, v36
	v_cmp_gt_f32_e32 vcc, s90, v34
	s_nop 1
	v_cndmask_b32_e64 v36, 0, 32, vcc
	v_ldexp_f32 v34, v34, v36
	v_log_f32_e32 v34, v34
	v_fmamk_f32 v36, v33, 0x3d800000, v37
	v_max_f32_e32 v33, v35, v35
	v_min_f32_e32 v33, 0, v33
	v_mul_f32_e32 v35, 0x3f317217, v34
	v_fma_f32 v35, v34, s91, -v35
	v_fmac_f32_e32 v35, 0x3377d1cf, v34
	v_fmac_f32_e32 v35, 0x3f317217, v34
	v_cmp_lt_f32_e64 s[36:37], |v34|, s92
	s_nop 1
	v_cndmask_b32_e64 v34, v34, v35, s[36:37]
	v_cndmask_b32_e32 v35, 0, v97, vcc
	v_sub_f32_e32 v34, v34, v35
	v_sub_f32_e32 v33, v33, v34
	v_fmamk_f32 v34, v33, 0x3d800000, v36
	ds_bpermute_b32 v33, v83, v34
	s_waitcnt lgkmcnt(0)
	v_cndmask_b32_e64 v33, v33, 0, s[8:9]
	v_add_f32_e32 v33, v33, v34
	ds_bpermute_b32 v35, v84, v33
	s_waitcnt lgkmcnt(0)
	v_cndmask_b32_e64 v35, 0, v35, s[10:11]
	v_add_f32_e32 v33, v35, v33
	v_sub_f32_e32 v35, v33, v34
	ds_bpermute_b32 v33, v85, v33
	v_add_f32_e32 v35, 0, v35
	v_add_f32_e32 v32, v32, v35
	v_add_f32_e32 v37, v37, v35
	ds_write2_b32 v38, v32, v37 offset1:132
	v_add_f32_e32 v32, v36, v35
	v_add_f32_e32 v34, v34, v35
	v_add_u32_e32 v35, 0x8c00, v98
	ds_write2_b32 v35, v32, v34 offset0:8 offset1:140
	v_mov_b32_e32 v32, 0
	v_mov_b32_e32 v34, 0
	v_mov_b32_e32 v35, 0
	v_mov_b32_e32 v36, 0
	v_mov_b32_e32 v37, 0
	v_mov_b32_e32 v38, 0
	s_and_saveexec_b64 s[36:37], s[6:7]
	s_cbranch_execz .LBB0_488
	ds_read_b128 v[34:37], v96 offset:1024
	ds_read_b128 v[38:41], v96 offset:1040
	s_waitcnt lgkmcnt(1)
	v_and_b32_sdwa v42, v35, v95 dst_sel:DWORD dst_unused:UNUSED_PAD src0_sel:WORD_1 src1_sel:DWORD
	v_and_b32_sdwa v43, v34, v95 dst_sel:DWORD dst_unused:UNUSED_PAD src0_sel:WORD_1 src1_sel:DWORD
	v_add3_u32 v44, v35, v42, s86
	v_add3_u32 v45, v34, v43, s86
	v_and_b32_e32 v43, 0xffff0000, v44
	v_and_b32_e32 v42, 0xffff0000, v45
	v_pk_add_f32 v[34:35], v[34:35], v[42:43] neg_lo:[0,1] neg_hi:[0,1]
	v_and_b32_sdwa v42, v37, v95 dst_sel:DWORD dst_unused:UNUSED_PAD src0_sel:WORD_1 src1_sel:DWORD
	v_and_b32_sdwa v43, v36, v95 dst_sel:DWORD dst_unused:UNUSED_PAD src0_sel:WORD_1 src1_sel:DWORD
	v_add3_u32 v46, v37, v42, s86
	v_add3_u32 v47, v36, v43, s86
	v_and_b32_e32 v43, 0xffff0000, v46
	v_and_b32_e32 v42, 0xffff0000, v47
	v_pk_add_f32 v[36:37], v[36:37], v[42:43] neg_lo:[0,1] neg_hi:[0,1]
	s_waitcnt lgkmcnt(0)
	v_and_b32_sdwa v42, v39, v95 dst_sel:DWORD dst_unused:UNUSED_PAD src0_sel:WORD_1 src1_sel:DWORD
	v_and_b32_sdwa v43, v38, v95 dst_sel:DWORD dst_unused:UNUSED_PAD src0_sel:WORD_1 src1_sel:DWORD
	v_add3_u32 v60, v39, v42, s86
	v_add3_u32 v61, v38, v43, s86
	v_and_b32_e32 v43, 0xffff0000, v60
	v_and_b32_e32 v42, 0xffff0000, v61
	v_pk_add_f32 v[38:39], v[38:39], v[42:43] neg_lo:[0,1] neg_hi:[0,1]
	v_and_b32_sdwa v42, v41, v95 dst_sel:DWORD dst_unused:UNUSED_PAD src0_sel:WORD_1 src1_sel:DWORD
	v_and_b32_sdwa v43, v40, v95 dst_sel:DWORD dst_unused:UNUSED_PAD src0_sel:WORD_1 src1_sel:DWORD
	v_add3_u32 v62, v41, v42, s86
	v_add3_u32 v63, v40, v43, s86
	v_and_b32_e32 v43, 0xffff0000, v62
	v_and_b32_e32 v42, 0xffff0000, v63
	v_pk_add_f32 v[40:41], v[40:41], v[42:43] neg_lo:[0,1] neg_hi:[0,1]
	v_bfe_u32 v42, v35, 16, 1
	v_bfe_u32 v43, v34, 16, 1
	v_bfe_u32 v64, v37, 16, 1
	v_bfe_u32 v65, v36, 16, 1
	v_bfe_u32 v66, v39, 16, 1
	v_bfe_u32 v67, v38, 16, 1
	v_bfe_u32 v68, v41, 16, 1
	v_bfe_u32 v69, v40, 16, 1
	v_add3_u32 v40, v40, v69, s86
	v_add3_u32 v41, v41, v68, s86
	v_add3_u32 v38, v38, v67, s86
	v_add3_u32 v39, v39, v66, s86
	v_add3_u32 v36, v36, v65, s86
	v_add3_u32 v37, v37, v64, s86
	v_add3_u32 v34, v34, v43, s86
	v_add3_u32 v35, v35, v42, s86
	v_perm_b32 v34, v35, v34, s88
	v_perm_b32 v35, v37, v36, s88
	v_perm_b32 v36, v39, v38, s88
	v_perm_b32 v37, v41, v40, s88
	v_perm_b32 v38, v44, v45, s88
	v_perm_b32 v39, v46, v47, s88
	v_perm_b32 v40, v60, v61, s88
	v_perm_b32 v41, v62, v63, s88

; __device__ __forceinline__ void phase_gla_pre(const Params& P, LAS unsigned char* lds, bool dry) {
;     ...
;         { const int ni = item + gridDim.x;
;           if (ni < 2048) { const int nbh = ni >> 6, nrow0 = (nbh >> 2) * SEQ + (ni & 63) * 64; const bf16_t* p_ = PJ + ((size_t)nbh * SEQ + (ni & 63) * 64 + te) * 128 + 16 * kc;
;             rq[0] = *(const u32x4*)(p_ + T_Q); rq[1] = *(const u32x4*)(p_ + T_Q + 8); rk[0] = *(const u32x4*)(p_ + T_K); rk[1] = *(const u32x4*)(p_ + T_K + 8);
;             if (tid < 256) rl = *(const f32x4*)(LR + (size_t)nrow0 * 16 + 4 * tid); } }
.LBB0_494:
	s_or_b64 exec, exec, s[36:37]
	s_add_i32 s82, s80, s38
	s_cmpk_gt_i32 s82, 0x7ff
	s_cselect_b64 s[36:37], -1, 0
	s_and_b64 vcc, exec, s[36:37]
	s_cbranch_vccnz .LBB0_498
	s_waitcnt vmcnt(4)
	v_mov_b32_e32 v4, v154
	v_mov_b32_e32 v5, v155
	v_mov_b32_e32 v6, v156
	v_mov_b32_e32 v7, v157
	v_mov_b32_e32 v8, v158
	v_mov_b32_e32 v9, v159
	v_mov_b32_e32 v10, v160
	v_mov_b32_e32 v11, v161
	v_mov_b32_e32 v12, v162
	v_mov_b32_e32 v13, v163
	v_mov_b32_e32 v14, v164
	v_mov_b32_e32 v15, v165
	v_mov_b32_e32 v16, v166
	v_mov_b32_e32 v17, v167
	v_mov_b32_e32 v18, v168
	v_mov_b32_e32 v19, v169
	s_and_saveexec_b64 s[42:43], s[4:5]
	s_cbranch_execz .LBB0_497
	v_mov_b32_e32 v0, v150
	v_mov_b32_e32 v1, v151
	v_mov_b32_e32 v2, v152
	v_mov_b32_e32 v3, v153

; #define LAS __attribute__((address_space(3)))
; __global__ void __launch_bounds__(512, 2) k_mega(Params P) {
;     extern __shared__ __attribute__((aligned(16))) unsigned char shm[];
;     LAS unsigned char* lds = (LAS unsigned char*)shm;
	.amdhsa_kernel _Z6k_mega6Params
		.amdhsa_group_segment_fixed_size 0
		.amdhsa_private_segment_fixed_size 0
		.amdhsa_kernarg_size 392
		.amdhsa_user_sgpr_count 2
		.amdhsa_user_sgpr_dispatch_ptr 0
		.amdhsa_user_sgpr_queue_ptr 0
		.amdhsa_user_sgpr_kernarg_segment_ptr 1
		.amdhsa_user_sgpr_dispatch_id 0
		.amdhsa_user_sgpr_kernarg_preload_length 0
		.amdhsa_user_sgpr_kernarg_preload_offset 0
		.amdhsa_user_sgpr_private_segment_size 0
		.amdhsa_uses_dynamic_stack 0
		.amdhsa_enable_private_segment 0
		.amdhsa_system_sgpr_workgroup_id_x 1
		.amdhsa_system_sgpr_workgroup_id_y 0
		.amdhsa_system_sgpr_workgroup_id_z 0
		.amdhsa_system_sgpr_workgroup_info 0
		.amdhsa_system_vgpr_workitem_id 2
		.amdhsa_next_free_vgpr 237
		.amdhsa_next_free_sgpr 102
		.amdhsa_accum_offset 240
		.amdhsa_reserve_vcc 1
		.amdhsa_float_round_mode_32 0
		.amdhsa_float_round_mode_16_64 0
		.amdhsa_float_denorm_mode_32 3
		.amdhsa_float_denorm_mode_16_64 3
		.amdhsa_dx10_clamp 1
		.amdhsa_ieee_mode 1
		.amdhsa_fp16_overflow 0
		.amdhsa_tg_split 0
		.amdhsa_exception_fp_ieee_invalid_op 0
		.amdhsa_exception_fp_denorm_src 0
		.amdhsa_exception_fp_ieee_div_zero 0
		.amdhsa_exception_fp_ieee_overflow 0
		.amdhsa_exception_fp_ieee_underflow 0
		.amdhsa_exception_fp_ieee_inexact 0
		.amdhsa_exception_int_div_zero 0
	.end_amdhsa_kernel

; #define LAS __attribute__((address_space(3)))
; __global__ void __launch_bounds__(512, 2) k_mega(Params P) {
;     extern __shared__ __attribute__((aligned(16))) unsigned char shm[];
;     LAS unsigned char* lds = (LAS unsigned char*)shm;
amdhsa.kernels:
  - .agpr_count:     0
    .args:
      - .offset:         0
        .size:           136
        .value_kind:     by_value
      - .offset:         136
        .size:           4
        .value_kind:     hidden_block_count_x
      - .offset:         140
        .size:           4
        .value_kind:     hidden_block_count_y
      - .offset:         144
        .size:           4
        .value_kind:     hidden_block_count_z
      - .offset:         148
        .size:           2
        .value_kind:     hidden_group_size_x
      - .offset:         150
        .size:           2
        .value_kind:     hidden_group_size_y
      - .offset:         152
        .size:           2
        .value_kind:     hidden_group_size_z
      - .offset:         154
        .size:           2
        .value_kind:     hidden_remainder_x
      - .offset:         156
        .size:           2
        .value_kind:     hidden_remainder_y
      - .offset:         158
        .size:           2
        .value_kind:     hidden_remainder_z
      - .offset:         176
        .size:           8
        .value_kind:     hidden_global_offset_x
      - .offset:         184
        .size:           8
        .value_kind:     hidden_global_offset_y
      - .offset:         192
        .size:           8
        .value_kind:     hidden_global_offset_z
      - .offset:         200
        .size:           2
        .value_kind:     hidden_grid_dims
      - .offset:         224
        .size:           8
        .value_kind:     hidden_multigrid_sync_arg
      - .offset:         256
        .size:           4
        .value_kind:     hidden_dynamic_lds_size
    .group_segment_fixed_size: 0
    .kernarg_segment_align: 8
    .kernarg_segment_size: 392
    .language:       OpenCL C
    .language_version:
      - 2
      - 0
    .max_flat_workgroup_size: 512
    .name:           _Z6k_mega6Params
    .private_segment_fixed_size: 0
    .sgpr_count:     108
    .sgpr_spill_count: 10
    .symbol:         _Z6k_mega6Params.kd
    .uniform_work_group_size: 1
    .uses_dynamic_stack: false
    .vgpr_count:     237
    .vgpr_spill_count: 0
    .wavefront_size: 64
